# merge rewrite + write-through (sc1) 16B epilogue stores in FFN-in/Z + FoX decay-load wait moved to consumer + diff-attention K-fragment reads hoisted
# speedup vs baseline: 1.0531x; 1.0141x over previous
.LBB0_1683:
	s_or_b64 exec, exec, s[0:1]
	s_add_i32 s0, 0, 0x11610
	v_mov_b32_e32 v0, s0
	v_readlane_b32 s0, v254, 29
	s_waitcnt lgkmcnt(0)
	s_barrier
	ds_read_b128 v[2:5], v0
	v_mov_b32_e32 v0, s0
	s_add_i32 s0, s23, 0x100
	s_lshr_b32 s0, s0, 6
	s_mul_hi_i32 s1, s8, 0x2c00000
	s_mul_i32 s8, s8, 0x2c00000
	s_add_u32 s10, s10, s8
	s_addc_u32 s1, s11, s1
	s_lshl_b32 s8, s9, 1
	s_add_u32 s10, s10, s8
	s_addc_u32 s11, s1, 0
	s_add_i32 s9, s0, -1
	s_mul_i32 s0, s9, 0x58000
	ds_read_b128 v[6:9], v0
	s_mul_hi_u32 s1, s9, 0x58000
	s_add_u32 s0, s10, s0
	v_ashrrev_i32_e32 v16, 3, v110
	s_movk_i32 s14, 0xb00
	v_lshlrev_b32_e32 v0, 3, v13
	s_addc_u32 s1, s11, s1
	v_mad_i64_i32 v[10:11], s[14:15], v16, s14, 0
	v_and_b32_e32 v0, 56, v0
	v_lshl_add_u64 v[18:19], v[10:11], 1, s[0:1]
	v_lshlrev_b32_e32 v0, 1, v0
	v_lshl_add_u64 v[18:19], v[18:19], 0, v[0:1]
	global_load_dwordx4 v[96:99], v[18:19], off offset:2048
	global_load_dwordx4 v[100:103], v[18:19], off offset:2560
	v_cmp_gt_i32_e64 s[0:1], 64, v110
	v_cmp_lt_i32_e32 vcc, 63, v110
	s_and_saveexec_b64 s[14:15], vcc
	s_xor_b64 s[14:15], exec, s[14:15]
	v_mov_b32_e32 v111, v1
	s_or_saveexec_b64 s[14:15], s[14:15]
	v_mov_b32_e32 v115, 0
	v_mov_b32_e32 v121, 0
	v_mov_b32_e32 v220, 0
	s_xor_b64 exec, exec, s[14:15]
	s_cbranch_execz .LBB0_1687
	s_lshl_b32 s16, s9, 6
	s_add_u32 s16, s12, s16
	s_addc_u32 s17, s13, 0
	v_ashrrev_i32_e32 v111, 31, v110
	v_lshl_add_u64 v[18:19], s[16:17], 0, v[110:111]
	v_lshl_add_u64 v[18:19], v[18:19], 4, s[2:3]
	s_lshl_b32 s94, s22, 2
	v_lshl_add_u64 v[18:19], v[18:19], 0, s[94:95]
	global_load_dword v220, v[18:19], off

.LBB0_1689:
	s_and_b32 s2, s18, 1
	s_mul_i32 s3, s2, 0x2400
	s_add_i32 s19, s3, 0
	s_mulk_i32 s2, 0xdd00
	s_add_i32 s16, s19, s2
	v_add3_u32 v0, s19, v123, v124
	s_waitcnt vmcnt(1)
	ds_write_b128 v0, v[96:99]
	s_waitcnt vmcnt(0)
	ds_write_b128 v0, v[100:103] offset:18432
	s_and_saveexec_b64 s[2:3], s[0:1]
	v_mul_f32_e32 v121, 0x3fb8aa3b, v220
	v_lshl_add_u32 v0, v110, 2, s16
	ds_write_b32 v0, v121 offset:36864
	s_or_b64 exec, exec, s[2:3]
	v_mov_b32_e32 v0, s16
	s_waitcnt lgkmcnt(0)
	s_barrier
	ds_read_b32 v0, v0 offset:37116
	s_waitcnt lgkmcnt(0)
	v_cmp_gt_f32_e32 vcc, v0, v122
	v_mov_b32_e32 v0, 17
	s_cbranch_vccnz .LBB0_1703
	s_cmp_lt_i32 s9, 1
	s_cbranch_scc1 .LBB0_1696
	s_add_i32 s2, s9, -1
	v_mad_u64_u32 v[2:3], s[2:3], s2, v230, v[116:117]
	global_load_dwordx4 v[96:99], v[2:3], off offset:2048
	global_load_dwordx4 v[100:103], v[2:3], off offset:2560
	s_and_saveexec_b64 s[2:3], s[0:1]
	s_cbranch_execz .LBB0_1695
	v_lshl_add_u64 v[2:3], v[118:119], 0, s[94:95]
	v_lshl_add_u64 v[2:3], v[2:3], 4, s[10:11]
	global_load_dword v220, v[2:3], off

.LBB0_1749:
	s_sub_i32 s0, s14, 63
	v_cmp_le_i32_e32 vcc, s0, v174
	s_and_saveexec_b64 s[6:7], vcc
	s_cbranch_execz .LBB0_1746
	v_add_u32_e32 v66, s15, v186
	v_add_u32_e32 v163, v66, v0
	ds_read_b128 v[82:85], v163
	ds_read_b128 v[86:89], v163 offset:4608
	ds_read_b128 v[90:93], v163 offset:32
	ds_read_b128 v[94:97], v163 offset:4640
	ds_read_b128 v[212:215], v163 offset:64
	ds_read_b128 v[220:223], v163 offset:4672
	ds_read_b128 v[240:243], v163 offset:96
	ds_read_b128 v[244:247], v163 offset:4704
	s_mov_b32 s69, s68
	s_mov_b32 s70, s68
	s_mov_b32 s71, s68
	s_mov_b32 s72, s68
	s_mov_b32 s73, s68
	s_mov_b32 s74, s68
	s_mov_b32 s75, s68
	s_mov_b32 s76, s68
	s_mov_b32 s77, s68
	s_mov_b32 s78, s68
	s_mov_b32 s79, s68
	s_mov_b32 s80, s68
	s_mov_b32 s81, s68
	s_mov_b32 s82, s68
	s_mov_b32 s83, s68
	v_mov_b64_e32 v[66:67], s[68:69]
	v_mov_b64_e32 v[68:69], s[70:71]
	v_mov_b64_e32 v[70:71], s[72:73]
	v_mov_b64_e32 v[72:73], s[74:75]
	v_mov_b64_e32 v[74:75], s[76:77]
	v_mov_b64_e32 v[76:77], s[78:79]
	v_mov_b64_e32 v[78:79], s[80:81]
	v_mov_b64_e32 v[80:81], s[82:83]
	v_cmp_gt_i32_e32 vcc, s14, v172
	s_waitcnt lgkmcnt(7)
	v_mfma_f32_32x32x16_bf16 v[114:129], v[82:85], v[130:133], v[66:81]
	s_waitcnt lgkmcnt(6)
	v_mfma_f32_32x32x16_bf16 v[98:113], v[86:89], v[130:133], v[66:81]
	s_waitcnt lgkmcnt(5)
	v_mfma_f32_32x32x16_bf16 v[114:129], v[90:93], v[134:137], v[114:129]
	s_nop 6
	v_add_u32_e32 v70, s14, v157
	v_subrev_u32_e32 v205, 63, v70
	v_subrev_u32_e32 v211, 31, v70
	v_subrev_u32_e32 v210, 30, v70
	v_subrev_u32_e32 v209, 61, v70
	v_subrev_u32_e32 v208, 29, v70
	s_waitcnt lgkmcnt(4)
	v_mfma_f32_32x32x16_bf16 v[98:113], v[94:97], v[134:137], v[98:113]
	v_subrev_u32_e32 v207, 60, v70
	v_subrev_u32_e32 v206, 28, v70
	v_subrev_u32_e32 v204, 55, v70
	v_subrev_u32_e32 v203, 23, v70
	v_subrev_u32_e32 v202, 54, v70
	v_subrev_u32_e32 v201, 22, v70
	v_subrev_u32_e32 v200, 53, v70
	v_subrev_u32_e32 v199, 21, v70
	v_subrev_u32_e32 v198, 52, v70
	v_subrev_u32_e32 v197, 20, v70
	v_subrev_u32_e32 v196, 47, v70
	v_add_u32_e32 v195, -15, v70
	v_subrev_u32_e32 v194, 46, v70
	v_add_u32_e32 v193, -14, v70
	v_subrev_u32_e32 v192, 45, v70
	v_add_u32_e32 v191, -13, v70
	v_subrev_u32_e32 v190, 44, v70
	v_add_u32_e32 v171, -12, v70
	v_subrev_u32_e32 v170, 39, v70
	v_add_u32_e32 v169, -7, v70
	v_subrev_u32_e32 v168, 38, v70
	v_add_u32_e32 v167, -6, v70
	v_subrev_u32_e32 v166, 37, v70
	v_add_u32_e32 v165, -5, v70
	v_subrev_u32_e32 v164, 36, v70
	v_add_u32_e32 v162, -4, v70
	s_and_saveexec_b64 s[8:9], vcc
	s_cbranch_execz .LBB0_1752
	v_cmp_le_i32_e64 s[0:1], v211, v156
	s_nop 1
	v_cndmask_b32_e64 v98, v236, v98, s[0:1]
	v_cmp_lt_i32_e64 s[0:1], v205, v156
	s_nop 1
	v_cndmask_b32_e64 v115, v236, v115, s[0:1]
	v_cmp_le_i32_e64 s[0:1], v205, v156
	s_nop 1
	v_cndmask_b32_e64 v114, v236, v114, s[0:1]
	v_cmp_le_i32_e64 s[0:1], v210, v156
	s_nop 1
	v_cndmask_b32_e64 v99, v236, v99, s[0:1]
	v_cmp_le_i32_e64 s[0:1], v209, v156
	s_nop 1
	v_cndmask_b32_e64 v116, v236, v116, s[0:1]
	v_cmp_le_i32_e64 s[0:1], v208, v156
	s_nop 1
	v_cndmask_b32_e64 v100, v236, v100, s[0:1]
	v_cmp_le_i32_e64 s[0:1], v207, v156
	s_nop 1
	v_cndmask_b32_e64 v117, v236, v117, s[0:1]
	v_cmp_le_i32_e64 s[0:1], v206, v156
	s_nop 1
	v_cndmask_b32_e64 v101, v236, v101, s[0:1]
	v_cmp_le_i32_e64 s[0:1], v204, v156
	s_nop 1
	v_cndmask_b32_e64 v118, v236, v118, s[0:1]
	v_cmp_le_i32_e64 s[0:1], v203, v156
	s_nop 1
	v_cndmask_b32_e64 v102, v236, v102, s[0:1]
	v_cmp_le_i32_e64 s[0:1], v202, v156
	s_nop 1
	v_cndmask_b32_e64 v119, v236, v119, s[0:1]
	v_cmp_le_i32_e64 s[0:1], v201, v156
	s_nop 1
	v_cndmask_b32_e64 v103, v236, v103, s[0:1]
	v_cmp_le_i32_e64 s[0:1], v200, v156
	s_nop 1
	v_cndmask_b32_e64 v120, v236, v120, s[0:1]
	v_cmp_le_i32_e64 s[0:1], v199, v156
	s_nop 1
	v_cndmask_b32_e64 v104, v236, v104, s[0:1]
	v_cmp_le_i32_e64 s[0:1], v198, v156
	s_nop 1
	v_cndmask_b32_e64 v121, v236, v121, s[0:1]
	v_cmp_le_i32_e64 s[0:1], v197, v156
	s_nop 1
	v_cndmask_b32_e64 v105, v236, v105, s[0:1]
	v_cmp_le_i32_e64 s[0:1], v196, v156
	s_nop 1
	v_cndmask_b32_e64 v122, v236, v122, s[0:1]
	v_cmp_le_i32_e64 s[0:1], v195, v156
	s_nop 1
	v_cndmask_b32_e64 v106, v236, v106, s[0:1]
	v_cmp_le_i32_e64 s[0:1], v194, v156
	s_nop 1
	v_cndmask_b32_e64 v123, v236, v123, s[0:1]
	v_cmp_le_i32_e64 s[0:1], v193, v156
	s_nop 1
	v_cndmask_b32_e64 v107, v236, v107, s[0:1]
	v_cmp_le_i32_e64 s[0:1], v192, v156
	s_nop 1
	v_cndmask_b32_e64 v124, v236, v124, s[0:1]
	v_cmp_le_i32_e64 s[0:1], v191, v156
	s_nop 1
	v_cndmask_b32_e64 v108, v236, v108, s[0:1]
	v_cmp_le_i32_e64 s[0:1], v190, v156
	s_nop 1
	v_cndmask_b32_e64 v125, v236, v125, s[0:1]
	v_cmp_le_i32_e64 s[0:1], v171, v156
	s_nop 1
	v_cndmask_b32_e64 v109, v236, v109, s[0:1]
	v_cmp_le_i32_e64 s[0:1], v170, v156
	s_nop 1
	v_cndmask_b32_e64 v126, v236, v126, s[0:1]
	v_cmp_le_i32_e64 s[0:1], v169, v156
	s_nop 1
	v_cndmask_b32_e64 v110, v236, v110, s[0:1]
	v_cmp_le_i32_e64 s[0:1], v168, v156
	s_nop 1
	v_cndmask_b32_e64 v127, v236, v127, s[0:1]
	v_cmp_le_i32_e64 s[0:1], v167, v156
	s_nop 1
	v_cndmask_b32_e64 v111, v236, v111, s[0:1]
	v_cmp_le_i32_e64 s[0:1], v166, v156
	s_nop 1
	v_cndmask_b32_e64 v128, v236, v128, s[0:1]
	v_cmp_le_i32_e64 s[0:1], v165, v156
	s_nop 1
	v_cndmask_b32_e64 v112, v236, v112, s[0:1]
	v_cmp_le_i32_e64 s[0:1], v164, v156
	s_nop 1
	v_cndmask_b32_e64 v129, v236, v129, s[0:1]
	v_cmp_le_i32_e64 s[0:1], v162, v156
	s_nop 1
	v_cndmask_b32_e64 v113, v236, v113, s[0:1]
.LBB0_1752:
	s_or_b64 exec, exec, s[8:9]
	v_mov_b64_e32 v[66:67], s[68:69]
	v_mov_b64_e32 v[68:69], s[70:71]
	v_mov_b64_e32 v[70:71], s[72:73]
	v_mov_b64_e32 v[72:73], s[74:75]
	v_mov_b64_e32 v[74:75], s[76:77]
	v_mov_b64_e32 v[76:77], s[78:79]
	v_mov_b64_e32 v[78:79], s[80:81]
	v_mov_b64_e32 v[80:81], s[82:83]
	s_waitcnt lgkmcnt(3)
	s_nop 0
	v_mfma_f32_32x32x16_bf16 v[82:97], v[212:215], v[138:141], v[66:81]
	s_waitcnt lgkmcnt(2)
	v_mfma_f32_32x32x16_bf16 v[66:81], v[220:223], v[138:141], v[66:81]
	s_waitcnt lgkmcnt(1)
	v_mfma_f32_32x32x16_bf16 v[82:97], v[240:243], v[142:145], v[82:97]
	s_waitcnt lgkmcnt(0)
	v_mfma_f32_32x32x16_bf16 v[66:81], v[244:247], v[142:145], v[66:81]
	s_and_saveexec_b64 s[0:1], vcc
	s_cbranch_execz .LBB0_1745
	v_cmp_le_i32_e32 vcc, v211, v156
	s_nop 8
	v_cndmask_b32_e32 v66, v236, v66, vcc
	v_cmp_lt_i32_e32 vcc, v205, v156
	s_nop 1
	v_cndmask_b32_e32 v83, v236, v83, vcc
	v_cmp_le_i32_e32 vcc, v205, v156
	s_nop 1
	v_cndmask_b32_e32 v82, v236, v82, vcc
	v_cmp_le_i32_e32 vcc, v210, v156
	s_nop 1
	v_cndmask_b32_e32 v67, v236, v67, vcc
	v_cmp_le_i32_e32 vcc, v209, v156
	s_nop 1
	v_cndmask_b32_e32 v84, v236, v84, vcc
	v_cmp_le_i32_e32 vcc, v208, v156
	s_nop 1
	v_cndmask_b32_e32 v68, v236, v68, vcc
	v_cmp_le_i32_e32 vcc, v207, v156
	s_nop 1
	v_cndmask_b32_e32 v85, v236, v85, vcc
	v_cmp_le_i32_e32 vcc, v206, v156
	s_nop 1
	v_cndmask_b32_e32 v69, v236, v69, vcc
	v_cmp_le_i32_e32 vcc, v204, v156
	s_nop 1
	v_cndmask_b32_e32 v86, v236, v86, vcc
	v_cmp_le_i32_e32 vcc, v203, v156
	s_nop 1
	v_cndmask_b32_e32 v70, v236, v70, vcc
	v_cmp_le_i32_e32 vcc, v202, v156
	s_nop 1
	v_cndmask_b32_e32 v87, v236, v87, vcc
	v_cmp_le_i32_e32 vcc, v201, v156
	s_nop 1
	v_cndmask_b32_e32 v71, v236, v71, vcc
	v_cmp_le_i32_e32 vcc, v200, v156
	s_nop 1
	v_cndmask_b32_e32 v88, v236, v88, vcc
	v_cmp_le_i32_e32 vcc, v199, v156
	s_nop 1
	v_cndmask_b32_e32 v72, v236, v72, vcc
	v_cmp_le_i32_e32 vcc, v198, v156
	s_nop 1
	v_cndmask_b32_e32 v89, v236, v89, vcc
	v_cmp_le_i32_e32 vcc, v197, v156
	s_nop 1
	v_cndmask_b32_e32 v73, v236, v73, vcc
	v_cmp_le_i32_e32 vcc, v196, v156
	s_nop 1
	v_cndmask_b32_e32 v90, v236, v90, vcc
	v_cmp_le_i32_e32 vcc, v195, v156
	s_nop 1
	v_cndmask_b32_e32 v74, v236, v74, vcc
	v_cmp_le_i32_e32 vcc, v194, v156
	s_nop 1
	v_cndmask_b32_e32 v91, v236, v91, vcc
	v_cmp_le_i32_e32 vcc, v193, v156
	s_nop 1
	v_cndmask_b32_e32 v75, v236, v75, vcc
	v_cmp_le_i32_e32 vcc, v192, v156
	s_nop 1
	v_cndmask_b32_e32 v92, v236, v92, vcc
	v_cmp_le_i32_e32 vcc, v191, v156
	s_nop 1
	v_cndmask_b32_e32 v76, v236, v76, vcc
	v_cmp_le_i32_e32 vcc, v190, v156
	s_nop 1
	v_cndmask_b32_e32 v93, v236, v93, vcc
	v_cmp_le_i32_e32 vcc, v171, v156
	s_nop 1
	v_cndmask_b32_e32 v77, v236, v77, vcc
	v_cmp_le_i32_e32 vcc, v170, v156
	s_nop 1
	v_cndmask_b32_e32 v94, v236, v94, vcc
	v_cmp_le_i32_e32 vcc, v169, v156
	s_nop 1
	v_cndmask_b32_e32 v78, v236, v78, vcc
	v_cmp_le_i32_e32 vcc, v168, v156
	s_nop 1
	v_cndmask_b32_e32 v95, v236, v95, vcc
	v_cmp_le_i32_e32 vcc, v167, v156
	s_nop 1
	v_cndmask_b32_e32 v79, v236, v79, vcc
	v_cmp_le_i32_e32 vcc, v166, v156
	s_nop 1
	v_cndmask_b32_e32 v96, v236, v96, vcc
	v_cmp_le_i32_e32 vcc, v165, v156
	s_nop 1
	v_cndmask_b32_e32 v80, v236, v80, vcc
	v_cmp_le_i32_e32 vcc, v164, v156
	s_nop 1
	v_cndmask_b32_e32 v97, v236, v97, vcc
	v_cmp_le_i32_e32 vcc, v162, v156
	s_nop 1
	v_cndmask_b32_e32 v81, v236, v81, vcc
	s_branch .LBB0_1745
